# v055 plus slc fast tile tail: each PV step's V-fragment LDS reads issued one step earlier (step 1 before the row max)
# speedup vs baseline: 1.0018x; 1.0006x over previous
; template <int MODE, bool MASK, bool WITH_O>
; DI void attn_tile_t(lptr Kt, lptr Vt, const bf16x8 (&qf)[4], f32x16& o0, f32x16& o1, RowState& rs, const TP& tp, int lane) {
;     const int hi = lane >> 5;
;     f32x16 s0, s1;
;     bias_init<MODE>(s0, s1, tp, tp.fb - rs.mref, hi);
;     qk_acc(Kt, qf, s0, s1, lane);
;     const float mx = mask_rowmax<MASK>(s0, s1, tp);
;     const bool was = rs.seen; rs.seen = was || (mx > -1e29f);
;     const bool trig = (mx > 8.f) || (!was && mx > -1e29f && mx < -8.f);
; DI void slc_unit(const Params& P, lptr L, int u, int tid, int lane, int wid) {
;     ...
;         const int j = (int)list[jt], kv0 = j * 64;
;         const bool sel = (sm[ql * 8 + (j >> 5)] >> (j & 31)) & 1u;
;         if (__any(sel)) {
;             TP tp; tp.cs = nullptr; tp.sl = sl; tp.fb = sl * (float)(kv0 + 8 * hi - t); tp.lim = t - kv0 - 8 * hi; tp.lim2 = -(1 << 30); tp.sel = sel;
;             attn_tile<1>(Kt, Vt, qf, o0, o1, rs, tp, true, lane);
.LBB0_613:
	v_mov_b32_e32 v0, v253
	s_and_b32 s31, s0, 1
	v_and_b32_e32 v35, 31, v253
	s_waitcnt lgkmcnt(0)
	v_lshrrev_b32_e32 v36, v0, v255
	v_bfe_u32 v34, v255, v35, 1
	v_and_b32_e32 v35, 1, v36
	v_mov_b32_e32 v253, v254
	v_cmp_ne_u32_e32 vcc, 0, v34
	v_cmp_eq_u32_e64 s[28:29], 1, v35
	s_cbranch_vccz .LBB0_618
	s_mul_i32 s33, s31, 0x2400
	v_add_u32_e32 v232, s33, v170
	ds_read_b128 v[102:105], v232 offset:4608
	ds_read_b128 v[106:109], v232
	ds_read_b128 v[110:113], v232 offset:32
	ds_read_b128 v[114:117], v232 offset:4640
	ds_read_b128 v[118:121], v232 offset:64
	ds_read_b128 v[158:161], v232 offset:4672
	ds_read_b128 v[162:165], v232 offset:96
	ds_read_b128 v[166:169], v232 offset:4704
	v_lshl_or_b32 v0, v0, 6, v126
	v_sub_u32_e32 v34, v0, v91
	v_cvt_f32_i32_e32 v34, v34
	s_mov_b32 s0, 2.0
	v_sub_u32_e32 v152, v91, v0
	s_mov_b32 s1, 0x40400000
	v_cmp_lt_i32_e32 vcc, 54, v152
	v_fma_f32 v0, v150, v34, -v101
	s_cmp_eq_u64 vcc, exec
	s_cselect_b64 s[98:99], -1, 0
	s_orn2_b64 s[100:101], s[28:29], s[98:99]
	v_cndmask_b32_e64 v0, v210, v0, s[100:101]
	v_pk_fma_f32 v[36:37], v[94:95], s[0:1], v[0:1] op_sel_hi:[1,1,0]
	s_mov_b32 s0, 4.0
	s_mov_b32 s1, 0x40a00000
	v_pk_fma_f32 v[38:39], v[94:95], s[0:1], v[0:1] op_sel_hi:[1,1,0]
	s_mov_b32 s0, 0x40c00000
	s_mov_b32 s1, 0x40e00000
	v_pk_fma_f32 v[40:41], v[94:95], s[0:1], v[0:1] op_sel_hi:[1,1,0]
	s_mov_b32 s0, 0x41800000
	s_mov_b32 s1, 0x41880000
	v_pk_fma_f32 v[42:43], v[94:95], s[0:1], v[0:1] op_sel_hi:[1,1,0]
	s_mov_b32 s0, 0x41900000
	s_mov_b32 s1, 0x41980000
	v_pk_fma_f32 v[44:45], v[94:95], s[0:1], v[0:1] op_sel_hi:[1,1,0]
	s_mov_b32 s0, 0x41a00000
	s_mov_b32 s1, 0x41a80000
	v_mov_b32_e32 v151, v150
	v_fma_f32 v34, 0, v150, v0
	v_add_f32_e32 v35, v150, v0
	v_pk_fma_f32 v[46:47], v[94:95], s[0:1], v[0:1] op_sel_hi:[1,1,0]
	v_pk_fma_f32 v[48:49], v[94:95], s[18:19], v[0:1] op_sel_hi:[1,1,0]
	v_pk_fma_f32 v[64:65], v[150:151], s[4:5], v[0:1] op_sel_hi:[1,1,0]
	v_pk_fma_f32 v[62:63], v[150:151], s[14:15], v[0:1] op_sel_hi:[1,1,0]
	v_pk_fma_f32 v[60:61], v[150:151], s[16:17], v[0:1] op_sel_hi:[1,1,0]
	v_pk_fma_f32 v[58:59], v[150:151], s[94:95], v[0:1] op_sel_hi:[1,1,0]
	v_pk_fma_f32 v[56:57], v[150:151], s[96:97], v[0:1] op_sel_hi:[1,1,0]
	v_pk_fma_f32 v[54:55], v[150:151], s[84:85], v[0:1] op_sel_hi:[1,1,0]
	v_pk_fma_f32 v[52:53], v[150:151], s[72:73], v[0:1] op_sel_hi:[1,1,0]
	v_pk_fma_f32 v[50:51], v[96:97], s[44:45], v[0:1] op_sel_hi:[1,1,0]
	s_setprio 1
	s_waitcnt lgkmcnt(6)
	v_mfma_f32_32x32x16_bf16 v[34:49], v[106:109], v[66:69], v[34:49]
	v_mfma_f32_32x32x16_bf16 v[50:65], v[102:105], v[66:69], v[50:65]
	s_waitcnt lgkmcnt(5)
	v_mfma_f32_32x32x16_bf16 v[34:49], v[110:113], v[70:73], v[34:49]
	s_waitcnt lgkmcnt(4)
	v_mfma_f32_32x32x16_bf16 v[50:65], v[114:117], v[70:73], v[50:65]
	s_waitcnt lgkmcnt(3)
	v_mfma_f32_32x32x16_bf16 v[34:49], v[118:121], v[74:77], v[34:49]
	s_waitcnt lgkmcnt(2)
	v_mfma_f32_32x32x16_bf16 v[50:65], v[158:161], v[74:77], v[50:65]
	s_waitcnt lgkmcnt(1)
	v_mfma_f32_32x32x16_bf16 v[34:49], v[162:165], v[78:81], v[34:49]
	s_waitcnt lgkmcnt(0)
	v_mfma_f32_32x32x16_bf16 v[50:65], v[166:169], v[78:81], v[50:65]
	s_setprio 0
	s_and_b64 vcc, exec, s[98:99]
	s_cbranch_vccz .Lslc_masked
	s_nop 10
	v_add_u32_e32 v233, s33, v172
	ds_read_b128 v[236:239], v233 offset:18432
	ds_read_b128 v[240:243], v233 offset:23040
	v_max_f32_e32 v252, v65, v65
	v_max_f32_e32 v228, v49, v49
	v_min_f32_e32 v252, v228, v252
	v_max3_f32 v228, v252, v34, v50
	v_max3_f32 v252, v252, v35, v51
	s_mov_b32 s0, 0xefa18f08
	v_max3_f32 v228, v228, v36, v52
	v_max3_f32 v252, v252, v37, v53
	s_nop 0
	v_max3_f32 v228, v228, v38, v54
	v_max3_f32 v252, v252, v39, v55
	s_nop 0
	v_max3_f32 v228, v228, v40, v56
	v_max3_f32 v252, v252, v41, v57
	s_nop 0
	v_max3_f32 v228, v228, v42, v58
	v_max3_f32 v252, v252, v43, v59
	s_nop 0
	v_max3_f32 v228, v228, v44, v60
	v_max3_f32 v252, v252, v45, v61
	s_nop 0
	v_max3_f32 v228, v228, v46, v62
	v_max3_f32 v252, v252, v47, v63
	s_nop 0
	v_max3_f32 v228, v228, v48, v64
	v_max3_f32 v252, v252, v49, v65
	s_nop 0
	v_max_f32_e32 v252, v252, v252
	v_max_f32_e32 v228, v228, v228
	v_max_f32_e32 v252, v228, v252
	v_mov_b32_e32 v228, v252
	s_nop 1
	v_permlane32_swap_b32_e32 v228, v252
	s_waitcnt lgkmcnt(0)
	v_max_f32_e32 v252, v252, v228
	v_cmp_lt_f32_e64 s[28:29], s0, v252
	s_mov_b32 s0, 0x41000000
	v_cmp_lt_f32_e32 vcc, s0, v252
	s_mov_b32 s0, 0xc1000000
	v_cmp_gt_f32_e64 s[0:1], s0, v252
	s_and_b64 s[0:1], s[0:1], s[28:29]
	s_andn2_b64 s[0:1], s[0:1], s[22:23]
	s_or_b64 s[0:1], s[0:1], vcc
	s_and_b64 vcc, exec, s[0:1]
	s_cbranch_vccnz .Lsf_rare
; template <int MODE, bool MASK, bool WITH_O>
; DI void attn_tile_t(lptr Kt, lptr Vt, const bf16x8 (&qf)[4], f32x16& o0, f32x16& o1, RowState& rs, const TP& tp, int lane) {
;     ...
;         const int i = lane & 31;
;         lptr vp = Vt + i * KPB + hi * 16;
;         float sum = 0.f;
;     ...
;         PV_STEP(s0, 0, 0) PV_STEP(s0, 8, 32) PV_STEP(s1, 0, 64) PV_STEP(s1, 8, 96)
;     ...
;         rs.l += sum;
	v_exp_f32_e32 v252, v34
	v_exp_f32_e32 v103, v35
	v_exp_f32_e32 v111, v36
	v_exp_f32_e32 v105, v37
	v_add_f32_e32 v106, 0, v252
	v_add_f32_e32 v106, v103, v106
	v_add_f32_e32 v104, v111, v106
	v_exp_f32_e32 v106, v38
	v_exp_f32_e32 v107, v39
	v_exp_f32_e32 v108, v40
	v_add_f32_e32 v104, v105, v104
	v_exp_f32_e32 v109, v41
	v_add_f32_e32 v104, v106, v104
	v_add_f32_e32 v104, v107, v104
	v_add_f32_e32 v104, v108, v104
	v_add_f32_e32 v110, v109, v104
	v_cvt_pk_bf16_f32 v104, v252, v103
	v_cvt_pk_bf16_f32 v105, v111, v105
	v_cvt_pk_bf16_f32 v106, v106, v107
	v_cvt_pk_bf16_f32 v107, v108, v109
	s_or_b64 s[22:23], s[22:23], s[28:29]
	s_waitcnt lgkmcnt(1)
	v_mfma_f32_32x32x16_bf16 v[18:33], v[236:239], v[104:107], v[18:33]
	s_waitcnt lgkmcnt(0)
	v_mfma_f32_32x32x16_bf16 v[2:17], v[240:243], v[104:107], v[2:17]
	v_exp_f32_e32 v252, v42
	v_exp_f32_e32 v43, v43
	ds_read_b128 v[236:239], v233 offset:18464
	ds_read_b128 v[240:243], v233 offset:23072
	v_exp_f32_e32 v103, v44
	v_exp_f32_e32 v44, v45
	v_add_f32_e32 v229, v252, v110
	v_exp_f32_e32 v45, v46
	v_add_f32_e32 v229, v43, v229
	v_exp_f32_e32 v46, v47
	v_add_f32_e32 v42, v103, v229
	v_exp_f32_e32 v47, v48
	v_add_f32_e32 v42, v44, v42
	v_exp_f32_e32 v48, v49
	v_add_f32_e32 v42, v45, v42
	v_add_f32_e32 v42, v46, v42
	v_add_f32_e32 v42, v47, v42
	v_add_f32_e32 v229, v48, v42
	v_cvt_pk_bf16_f32 v42, v252, v43
	v_cvt_pk_bf16_f32 v43, v103, v44
	v_cvt_pk_bf16_f32 v44, v45, v46
	v_cvt_pk_bf16_f32 v45, v47, v48
	s_waitcnt lgkmcnt(1)
	s_nop 0
	v_mfma_f32_32x32x16_bf16 v[18:33], v[236:239], v[42:45], v[18:33]
	s_waitcnt lgkmcnt(0)
	v_mfma_f32_32x32x16_bf16 v[2:17], v[240:243], v[42:45], v[2:17]
	v_exp_f32_e32 v230, v50
	v_exp_f32_e32 v51, v51
	ds_read_b128 v[42:45], v233 offset:18496
	ds_read_b128 v[46:49], v233 offset:23104
	v_exp_f32_e32 v231, v52
	v_exp_f32_e32 v52, v53
	v_add_f32_e32 v229, v230, v229
	v_exp_f32_e32 v53, v54
	v_add_f32_e32 v229, v51, v229
	v_exp_f32_e32 v54, v55
	v_add_f32_e32 v50, v231, v229
	v_exp_f32_e32 v55, v56
	v_add_f32_e32 v50, v52, v50
	v_exp_f32_e32 v41, v57
	v_add_f32_e32 v50, v53, v50
	v_add_f32_e32 v50, v54, v50
	v_add_f32_e32 v50, v55, v50
	v_add_f32_e32 v56, v41, v50
	v_cvt_pk_bf16_f32 v50, v230, v51
	v_cvt_pk_bf16_f32 v51, v231, v52
	v_cvt_pk_bf16_f32 v52, v53, v54
	v_cvt_pk_bf16_f32 v53, v55, v41
	s_waitcnt lgkmcnt(1)
	s_nop 0
	v_mfma_f32_32x32x16_bf16 v[18:33], v[42:45], v[50:53], v[18:33]
	s_waitcnt lgkmcnt(0)
	v_mfma_f32_32x32x16_bf16 v[2:17], v[46:49], v[50:53], v[2:17]
	v_exp_f32_e32 v38, v58
	v_exp_f32_e32 v34, v59
	ds_read_b128 v[42:45], v233 offset:18528
	ds_read_b128 v[46:49], v233 offset:23136
	v_exp_f32_e32 v0, v60
	v_exp_f32_e32 v35, v61
	v_add_f32_e32 v41, v38, v56
	v_exp_f32_e32 v36, v62
	v_add_f32_e32 v41, v34, v41
	v_exp_f32_e32 v37, v63
	v_exp_f32_e32 v39, v64
	v_exp_f32_e32 v40, v65
	v_add_f32_e32 v41, v0, v41
	v_add_f32_e32 v41, v35, v41
	v_add_f32_e32 v41, v36, v41
	v_add_f32_e32 v41, v37, v41
	v_cvt_pk_bf16_f32 v34, v38, v34
	v_cvt_pk_bf16_f32 v35, v0, v35
	v_cvt_pk_bf16_f32 v36, v36, v37
	v_cvt_pk_bf16_f32 v37, v39, v40
	v_add_f32_e32 v41, v39, v41
	v_add_f32_e32 v41, v40, v41
	s_waitcnt lgkmcnt(1)
	v_mfma_f32_32x32x16_bf16 v[18:33], v[42:45], v[34:37], v[18:33]
	s_waitcnt lgkmcnt(0)
	v_mfma_f32_32x32x16_bf16 v[2:17], v[46:49], v[34:37], v[2:17]
	v_add_f32_e32 v100, v100, v41
	s_branch .LBB0_618
